# s5_scan: each wave touches its 64 KB chunk-state slab once at phase start (8 discarded loads) so the 8 sequential batch loads hit L2 instead of memory
# baseline (speedup 1.0000x reference)
.LBB0_320:
	s_or_b64 exec, exec, s[4:5]
	s_mov_b64 s[12:13], s[84:85]
	s_waitcnt lgkmcnt(0)
	s_barrier
	v_mbcnt_lo_u32_b32 v0, -1, 0
	v_mbcnt_hi_u32_b32 v0, -1, v0
	s_getreg_b32 s2, hwreg(HW_REG_HW_ID, 0, 6)
	s_lshl_b32 s2, s2, 2
	s_and_b32 s2, s2, 0xfc
	s_add_i32 s2, s2, 0
	s_add_i32 s2, s2, 0x23400
	v_mov_b32_e32 v2, s2
	ds_read_b32 v2, v2
	v_readlane_b32 s3, v255, 2
	s_waitcnt lgkmcnt(0)
	v_readfirstlane_b32 s2, v2
	s_lshl_b32 s2, s2, 6
	s_add_i32 s2, s2, s3
	v_add_u32_e32 v3, s2, v0
	s_mov_b32 s2, 0x8000
	v_cmp_gt_i32_e32 vcc, s2, v3
	s_and_saveexec_b64 s[10:11], vcc
	s_cbranch_execz .LBB0_326
	s_load_dwordx2 s[100:101], s[12:13], 0x110
	v_bfe_u32 v100, v3, 6, 6
	v_lshrrev_b32_e32 v101, 12, v3
	v_lshlrev_b32_e32 v100, 10, v100
	v_lshl_add_u32 v100, v101, 7, v100
	v_and_b32_e32 v101, 63, v0
	v_lshlrev_b32_e32 v101, 7, v101
	v_lshl_add_u32 v100, v100, 9, v101
	s_waitcnt lgkmcnt(0)
	s_add_u32 s100, s100, 0x16d00000
	s_addc_u32 s101, s101, 0
	global_load_dword v102, v100, s[100:101]
	v_add_u32_e32 v100, 0x2000, v100
	global_load_dword v102, v100, s[100:101]
	v_add_u32_e32 v100, 0x2000, v100
	global_load_dword v102, v100, s[100:101]
	v_add_u32_e32 v100, 0x2000, v100
	global_load_dword v102, v100, s[100:101]
	v_add_u32_e32 v100, 0x2000, v100
	global_load_dword v102, v100, s[100:101]
	v_add_u32_e32 v100, 0x2000, v100
	global_load_dword v102, v100, s[100:101]
	v_add_u32_e32 v100, 0x2000, v100
	global_load_dword v102, v100, s[100:101]
	v_add_u32_e32 v100, 0x2000, v100
	global_load_dword v102, v100, s[100:101]
	s_load_dwordx2 s[2:3], s[12:13], 0xc8
	s_load_dwordx4 s[4:7], s[12:13], 0xb8
	v_bfe_u32 v4, v3, 6, 6
	v_readlane_b32 s8, v255, 17
	v_and_b32_e32 v2, 63, v0
	v_readlane_b32 s9, v255, 18
	v_or_b32_e32 v0, s8, v4
	s_waitcnt lgkmcnt(0)
	v_lshl_add_u64 v[6:7], v[0:1], 2, s[2:3]
	global_load_dword v5, v[6:7], off
	v_lshlrev_b64 v[6:7], 8, v[0:1]
	v_lshl_or_b32 v6, v2, 2, v6
	v_lshl_add_u64 v[8:9], s[6:7], 0, v[6:7]
	global_load_dword v0, v[8:9], off
	v_lshl_add_u64 v[6:7], s[4:5], 0, v[6:7]
	global_load_dword v7, v[6:7], off
	s_waitcnt vmcnt(2)
	v_mul_f32_e32 v5, 0x3fb8aa3b, v5
	v_exp_f32_e32 v8, v5
	s_waitcnt vmcnt(1)
	v_mul_f32_e32 v0, 0x42000000, v0
	v_mul_f32_e32 v5, v8, v0
	v_and_b32_e32 v6, 0x7fffffff, v5
	v_cmp_nlt_f32_e64 s[2:3], |v5|, s88
	s_and_saveexec_b64 s[4:5], s[2:3]
	s_xor_b64 s[14:15], exec, s[4:5]
	s_cbranch_execz .LBB0_323
	v_lshrrev_b32_e32 v0, 23, v6
	v_add_u32_e32 v0, 0xffffff88, v0
	v_cmp_lt_u32_e32 vcc, 63, v0
	s_nop 1
	v_cndmask_b32_e32 v9, 0, v227, vcc
	v_add_u32_e32 v0, v9, v0
	v_cmp_lt_u32_e64 s[4:5], 31, v0
	s_nop 1
	v_cndmask_b32_e64 v9, 0, v228, s[4:5]
	v_add_u32_e32 v0, v9, v0
	v_cmp_lt_u32_e64 s[6:7], 31, v0
	s_nop 1
	v_cndmask_b32_e64 v9, 0, v228, s[6:7]
	v_add_u32_e32 v9, v9, v0
	v_and_b32_e32 v0, 0x7fffff, v6
	v_or_b32_e32 v22, 0x800000, v0
	v_mad_u64_u32 v[10:11], s[2:3], v22, s89, 0
	v_mov_b32_e32 v0, v11
	v_mad_u64_u32 v[12:13], s[2:3], v22, s90, v[0:1]
	v_mov_b32_e32 v0, v13
	v_mad_u64_u32 v[14:15], s[2:3], v22, s91, v[0:1]
	v_mov_b32_e32 v0, v15
	v_mad_u64_u32 v[16:17], s[2:3], v22, s92, v[0:1]
	v_mov_b32_e32 v0, v17
	v_mad_u64_u32 v[18:19], s[2:3], v22, s93, v[0:1]
	v_mov_b32_e32 v0, v19
	v_mad_u64_u32 v[20:21], s[2:3], v22, s94, v[0:1]
	v_mov_b32_e32 v0, v21
	v_mad_u64_u32 v[22:23], s[2:3], v22, s95, v[0:1]
	v_cndmask_b32_e32 v11, v20, v16, vcc
	v_cndmask_b32_e32 v0, v22, v18, vcc
	v_cndmask_b32_e32 v15, v23, v20, vcc
	v_cndmask_b32_e64 v13, v0, v11, s[4:5]
	v_cndmask_b32_e64 v0, v15, v0, s[4:5]
	v_cndmask_b32_e32 v15, v18, v14, vcc
	v_cndmask_b32_e64 v11, v11, v15, s[4:5]
	v_cndmask_b32_e64 v0, v0, v13, s[6:7]
	v_cndmask_b32_e64 v13, v13, v11, s[6:7]
	v_sub_u32_e32 v17, 32, v9
	v_alignbit_b32 v18, v0, v13, v17
	v_cmp_eq_u32_e64 s[8:9], 0, v9
	v_cndmask_b32_e32 v10, v14, v10, vcc
	s_nop 0
	v_cndmask_b32_e64 v9, v18, v0, s[8:9]
	v_cndmask_b32_e32 v0, v16, v12, vcc
	v_cndmask_b32_e64 v12, v15, v0, s[4:5]
	v_cndmask_b32_e64 v11, v11, v12, s[6:7]
	v_alignbit_b32 v15, v13, v11, v17
	v_cndmask_b32_e64 v13, v15, v13, s[8:9]
	v_bfe_u32 v18, v9, 29, 1
	v_cndmask_b32_e64 v0, v0, v10, s[4:5]
	v_alignbit_b32 v15, v9, v13, 30
	v_sub_u32_e32 v19, 0, v18
	v_cndmask_b32_e64 v0, v12, v0, s[6:7]
	v_xor_b32_e32 v15, v15, v19
	v_alignbit_b32 v10, v11, v0, v17
	v_cndmask_b32_e64 v10, v10, v11, s[8:9]
	v_ffbh_u32_e32 v12, v15
	v_alignbit_b32 v11, v13, v10, 30
	v_min_u32_e32 v12, 32, v12
	v_alignbit_b32 v0, v10, v0, 30
	v_xor_b32_e32 v11, v11, v19
	v_sub_u32_e32 v13, 31, v12
	v_xor_b32_e32 v0, v0, v19
	v_alignbit_b32 v14, v15, v11, v13
	v_alignbit_b32 v0, v11, v0, v13
	v_alignbit_b32 v10, v14, v0, 9
	v_ffbh_u32_e32 v11, v10
	v_min_u32_e32 v11, 32, v11
	v_lshrrev_b32_e32 v16, 29, v9
	v_not_b32_e32 v13, v11
	v_alignbit_b32 v0, v10, v0, v13
	v_lshlrev_b32_e32 v10, 31, v16
	v_or_b32_e32 v13, 0x33000000, v10
	v_add_lshl_u32 v11, v11, v12, 23
	v_lshrrev_b32_e32 v0, 9, v0
	v_sub_u32_e32 v11, v13, v11
	v_or_b32_e32 v10, 0.5, v10
	v_lshlrev_b32_e32 v12, 23, v12
	v_or_b32_e32 v0, v11, v0
	v_lshrrev_b32_e32 v11, 9, v14
	v_sub_u32_e32 v10, v10, v12
	v_or_b32_e32 v10, v11, v10
	v_mul_f32_e32 v11, 0x3fc90fda, v10
	v_fma_f32 v12, v10, s96, -v11
	v_fmac_f32_e32 v12, 0x33a22168, v10
	v_fmac_f32_e32 v12, 0x3fc90fda, v0
	v_lshrrev_b32_e32 v9, 30, v9
	v_add_f32_e32 v0, v11, v12
	v_add_u32_e32 v9, v18, v9
